# phase E unit queue: next ticket requested early while ticket < 1280 (long-unit part of the queue), tail taken on demand as before
# baseline (speedup 1.0000x reference)
; #define LAS __attribute__((address_space(3)))
; __device__ __forceinline__ float wave_max(float v) { v = fmaxf(v, __shfl_xor(v, 1)); v = fmaxf(v, __shfl_xor(v, 2)); v = fmaxf(v, __shfl_xor(v, 4)); v = fmaxf(v, __shfl_xor(v, 8)); v = fmaxf(v, __shfl_xor(v, 16)); v = fmaxf(v, __shfl_xor(v, 32)); return v; }
; #define INP(k) ({ int k_ = (k); LAUNDER_S(k_); (const float*)(const GAS float*)P.in[k_]; })
; __global__ void __launch_bounds__(512, 2) hybrid_fwd(Params P) {
;     ...
;             LAS unsigned* misc = (LAS unsigned*)(lds + ATT_MISC); LAS float* btab = (LAS float*)(lds + ATT_BT);
;             const float* rel_bias = INP(1);
;             __syncthreads();
;             if (wave == 0) { const float* mqn = INP(4) + L * 64; const float* mkn = INP(5) + L * 64; const float* nqn = INP(6) + L * 64; const float* nkn = INP(7) + L * 192;
;                 float gq = fmaxf(fabsf(mqn[lane]), fabsf(nqn[lane])); float gk = fmaxf(fmaxf(fabsf(mkn[lane]), fabsf(nkn[lane])), fmaxf(fabsf(nkn[64 + lane]), fabsf(nkn[128 + lane])));
;                 float bm = 0.f;
; #pragma unroll
;                 for (int i = 0; i < 6; ++i) bm = fmaxf(bm, fabsf(rel_bias[lane + 64 * i]));
;                 gq = wave_max(gq); gk = wave_max(gk); bm = wave_max(bm);
;                 if (lane == 0) ((LAS float*)misc)[2] = 8.0f * gq * gk + bm; }
.LBB0_794:
	s_nop 0
	s_nop 0
	s_nop 0
	s_nop 0
	s_or_b64 exec, exec, s[4:5]
	v_readlane_b32 s4, v255, 17
	s_mov_b64 s[6:7], s[58:59]
	s_mov_b32 s5, s69
	s_barrier
	s_mov_b32 s5, s2
	v_mov_b32_e32 v210, v146
	s_mov_b32 s8, 1
	s_ashr_i32 s9, s8, 31
	s_lshl_b64 s[8:9], s[8:9], 3
	s_add_u32 s8, s0, s8
	s_addc_u32 s9, s1, s9
	s_load_dwordx2 s[8:9], s[8:9], 0x0
	s_waitcnt lgkmcnt(0)
	v_lshlrev_b32_e32 v253, 2, v210
	v_cmp_gt_u32_e32 vcc, 0x180, v210
	s_and_saveexec_b64 s[98:99], vcc
	global_load_dword v252, v253, s[8:9]
	s_mov_b64 exec, s[98:99]
	s_nop 3
	v_readfirstlane_b32 s5, v210
	s_cmp_lt_u32 s5, 64
	s_waitcnt lgkmcnt(0)
	s_barrier
	s_cbranch_scc0 .LBB0_798
	s_mov_b32 s10, 4
	s_ashr_i32 s11, s10, 31
	s_lshl_b64 s[10:11], s[10:11], 3
	s_add_u32 s10, s0, s10
	s_addc_u32 s11, s1, s11
	s_load_dwordx2 s[12:13], s[10:11], 0x0
	s_lshl_b32 s10, s4, 6
	s_ashr_i32 s11, s10, 31
	s_lshl_b64 s[10:11], s[10:11], 2
	s_mov_b32 s14, 5
	s_waitcnt lgkmcnt(0)
	s_add_u32 s12, s12, s10
	s_addc_u32 s13, s13, s11
	s_ashr_i32 s15, s14, 31
	s_lshl_b64 s[14:15], s[14:15], 3
	s_add_u32 s14, s0, s14
	s_addc_u32 s15, s1, s15
	s_load_dwordx2 s[14:15], s[14:15], 0x0
	s_mov_b32 s16, 6
	v_and_b32_e32 v0, 63, v210
	v_lshlrev_b32_e32 v1, 2, v0
	s_waitcnt lgkmcnt(0)
	s_add_u32 s18, s14, s10
	s_addc_u32 s19, s15, s11
	s_ashr_i32 s17, s16, 31
	s_lshl_b64 s[14:15], s[16:17], 3
	s_add_u32 s14, s0, s14
	s_addc_u32 s15, s1, s15
	s_load_dwordx2 s[14:15], s[14:15], 0x0
	s_mov_b32 s16, 7
	global_load_dword v2, v1, s[18:19]
	global_load_dword v3, v1, s[8:9]
	global_load_dword v4, v1, s[8:9] offset:256
	global_load_dword v5, v1, s[8:9] offset:512
	global_load_dword v6, v1, s[8:9] offset:768
	global_load_dword v7, v1, s[8:9] offset:1024
	global_load_dword v8, v1, s[8:9] offset:1280
	global_load_dword v9, v1, s[12:13]
	s_mul_i32 s12, s4, 0xc0
	s_waitcnt lgkmcnt(0)
	s_add_u32 s10, s14, s10
	s_addc_u32 s11, s15, s11
	s_ashr_i32 s17, s16, 31
	global_load_dword v10, v1, s[10:11]
	s_lshl_b64 s[10:11], s[16:17], 3
	s_add_u32 s10, s0, s10
	s_addc_u32 s11, s1, s11
	s_load_dwordx2 s[10:11], s[10:11], 0x0
	s_ashr_i32 s13, s12, 31
	s_lshl_b64 s[12:13], s[12:13], 2
	v_mbcnt_hi_u32_b32 v13, -1, v167
	v_and_b32_e32 v15, 64, v13
	s_waitcnt lgkmcnt(0)
	s_add_u32 s10, s10, s12
	s_addc_u32 s11, s11, s13
	global_load_dword v11, v1, s[10:11] offset:512
	global_load_dword v12, v1, s[10:11] offset:256
	s_nop 0
	global_load_dword v1, v1, s[10:11]
	v_xor_b32_e32 v14, 1, v13
	v_add_u32_e32 v15, 64, v15
	v_cmp_lt_i32_e32 vcc, v14, v15
	v_xor_b32_e32 v16, 2, v13
	v_xor_b32_e32 v17, 4, v13
	v_cndmask_b32_e32 v14, v13, v14, vcc
	v_lshlrev_b32_e32 v14, 2, v14
	v_cmp_lt_i32_e32 vcc, v16, v15
	v_xor_b32_e32 v18, 8, v13
	v_xor_b32_e32 v19, 16, v13
	v_cndmask_b32_e32 v16, v13, v16, vcc
	v_cmp_lt_i32_e32 vcc, v17, v15
	v_xor_b32_e32 v20, 32, v13
	s_waitcnt vmcnt(9)
	v_max3_f32 v3, |v3|, 0, |v4|
	v_cndmask_b32_e32 v17, v13, v17, vcc
	s_waitcnt vmcnt(7)
	v_max3_f32 v3, v3, |v5|, |v6|
	v_cmp_lt_i32_e32 vcc, v18, v15
	s_waitcnt vmcnt(5)
	v_max3_f32 v3, v3, |v7|, |v8|
	ds_bpermute_b32 v4, v14, v3
	v_cndmask_b32_e32 v18, v13, v18, vcc
	v_cmp_lt_i32_e32 vcc, v19, v15
	s_waitcnt vmcnt(4)
	v_max_f32_e64 v6, |v9|, |v9|
	v_lshlrev_b32_e32 v5, 2, v18
	s_waitcnt lgkmcnt(0)
	v_max_f32_e32 v4, v4, v4
	v_cndmask_b32_e32 v19, v13, v19, vcc
	v_cmp_lt_i32_e32 vcc, v20, v15
	v_lshlrev_b32_e32 v15, 2, v16
	v_max_f32_e32 v3, v3, v4
	ds_bpermute_b32 v4, v15, v3
	s_waitcnt vmcnt(3)
	v_max_f32_e64 v7, |v10|, |v10|
	v_max_f32_e32 v6, v6, v7
	ds_bpermute_b32 v7, v14, v6
	v_lshlrev_b32_e32 v16, 2, v17
	s_waitcnt lgkmcnt(1)
	v_max_f32_e32 v4, v4, v4
	v_max_f32_e32 v3, v3, v4
	s_waitcnt vmcnt(2)
	v_max_f32_e64 v4, |v11|, |v11|
	s_waitcnt vmcnt(1)
	v_max_f32_e64 v10, |v12|, |v12|
	v_max_f32_e32 v4, v10, v4
	s_waitcnt vmcnt(0)
	v_max3_f32 v1, |v2|, |v1|, v4
	ds_bpermute_b32 v2, v14, v1
	s_waitcnt lgkmcnt(1)
	v_max_f32_e32 v7, v7, v7
	v_max_f32_e32 v6, v6, v7
	ds_bpermute_b32 v7, v15, v6
	ds_bpermute_b32 v11, v16, v3
	s_waitcnt lgkmcnt(2)
	v_max_f32_e32 v2, v2, v2
	v_max_f32_e32 v1, v1, v2
	ds_bpermute_b32 v2, v15, v1
	s_waitcnt lgkmcnt(2)
	v_max_f32_e32 v4, v7, v7
	v_max_f32_e32 v4, v6, v4
	s_waitcnt lgkmcnt(1)
	v_max_f32_e32 v6, v11, v11
	ds_bpermute_b32 v7, v16, v4
	s_waitcnt lgkmcnt(1)
	v_max_f32_e32 v2, v2, v2
	v_max_f32_e32 v1, v1, v2
	v_max_f32_e32 v3, v3, v6
	ds_bpermute_b32 v2, v16, v1
	ds_bpermute_b32 v6, v5, v3
	s_waitcnt lgkmcnt(2)
	v_max_f32_e32 v7, v7, v7
	v_max_f32_e32 v4, v4, v7
	ds_bpermute_b32 v7, v5, v4
	s_waitcnt lgkmcnt(2)
	v_max_f32_e32 v2, v2, v2
	s_waitcnt lgkmcnt(1)
	v_max_f32_e32 v6, v6, v6
	v_max_f32_e32 v1, v1, v2
	v_lshlrev_b32_e32 v8, 2, v19
	v_max_f32_e32 v3, v3, v6
	ds_bpermute_b32 v2, v5, v1
	ds_bpermute_b32 v6, v8, v3
	s_waitcnt lgkmcnt(2)
	v_max_f32_e32 v5, v7, v7
	v_max_f32_e32 v4, v4, v5
	v_cndmask_b32_e32 v13, v13, v20, vcc
	s_waitcnt lgkmcnt(1)
	v_max_f32_e32 v2, v2, v2
	s_waitcnt lgkmcnt(0)
	v_max_f32_e32 v5, v6, v6
	ds_bpermute_b32 v6, v8, v4
	v_max_f32_e32 v2, v1, v2
	ds_bpermute_b32 v7, v8, v2
	v_max_f32_e32 v1, v3, v5
	v_lshlrev_b32_e32 v9, 2, v13
	s_waitcnt lgkmcnt(1)
	v_max_f32_e32 v3, v6, v6
	v_max_f32_e32 v3, v4, v3
	s_waitcnt lgkmcnt(0)
	v_max_f32_e32 v4, v7, v7
	v_max_f32_e32 v2, v2, v4
	ds_bpermute_b32 v5, v9, v3
	ds_bpermute_b32 v4, v9, v2
	ds_bpermute_b32 v6, v9, v1
	v_cmp_eq_u32_e32 vcc, 0, v0
	s_and_saveexec_b64 s[10:11], vcc
	s_cbranch_execz .LBB0_797
	s_waitcnt lgkmcnt(2)
	v_max_f32_e32 v0, v5, v5
	v_max_f32_e32 v3, v3, v3
	v_max_f32_e32 v0, v3, v0
	s_waitcnt lgkmcnt(1)
	v_max_f32_e32 v3, v4, v4
	v_max_f32_e32 v2, v2, v2
	v_max_f32_e32 v2, v2, v3
	s_waitcnt lgkmcnt(0)
	v_max_f32_e32 v3, v6, v6
	v_max_f32_e32 v1, v1, v1
	v_mul_f32_e32 v0, 0x41000000, v0
	v_max_f32_e32 v1, v1, v3
	v_fmac_f32_e32 v1, v0, v2
	ds_write_b32 v165, v1 offset:50696

; __global__ void __launch_bounds__(512, 2) hybrid_fwd(Params P) {
;     ...
;             for (int rep_ = 0; rep_ < REP_E; ++rep_) {
;             unsigned* ctl = (unsigned*)(ws + WS_CTL) + L + 2 * rep_;
;             unsigned char* HBUF = ws + WS_B; bf16_t* OMIX = (bf16_t*)(ws + WS_H);
.LBB0_805:
	s_or_b64 exec, exec, s[10:11]
	s_mov_b32 s5, 0
	v_writelane_b32 v255, s5, 63
	s_ashr_i32 s5, s4, 31
	s_lshl_b64 s[4:5], s[4:5], 2
	s_add_u32 s38, s6, s4
	s_addc_u32 s39, s7, s5
	s_add_u32 s28, s6, 0x13100000
	s_addc_u32 s40, s7, 0
	s_add_u32 s42, s6, 0x3100000
	s_addc_u32 s43, s7, 0
	s_add_u32 s41, s6, 0x14100000
	s_addc_u32 s46, s7, 0
	s_add_u32 s47, s6, 0x15100000
	s_addc_u32 s48, s7, 0
	s_add_u32 s4, s6, 0x2401000
	v_writelane_b32 v255, s4, 18
	s_addc_u32 s4, s7, 0
	s_add_u32 s49, s6, 0x16100000
	s_addc_u32 s50, s7, 0
	s_add_u32 s51, s6, 0x17100000
	s_addc_u32 s52, s7, 0
	s_add_u32 s53, s6, 0x18100000
	s_addc_u32 s54, s7, 0
	s_add_u32 s55, s6, 0x2d00000
	s_addc_u32 s60, s7, 0
	s_add_u32 s24, s6, 0x2d80000
	s_addc_u32 s25, s7, 0
	v_writelane_b32 v255, s4, 19
	s_add_u32 s4, s6, 0x2e00000
	s_addc_u32 s5, s7, 0
	v_writelane_b32 v255, s4, 20
	v_cmp_eq_u32_e64 s[44:45], 0, v210
	s_waitcnt lgkmcnt(0)
	v_writelane_b32 v255, s5, 21
	s_add_u32 s4, s6, 0x19100000
	s_addc_u32 s5, s7, 0
	v_writelane_b32 v255, s4, 22
	s_add_u32 s26, s6, 0x1c100000
	s_barrier
	v_writelane_b32 v255, s5, 23
	s_addc_u32 s4, s7, 0
	v_writelane_b32 v255, s4, 24
	s_add_u32 s4, s6, 0x1c900000
	v_writelane_b32 v255, s4, 25
	s_addc_u32 s4, s7, 0
	v_writelane_b32 v255, s4, 26
	s_add_u32 s4, s6, 0x1d100000
	v_writelane_b32 v255, s4, 27
	s_addc_u32 s4, s7, 0
	v_writelane_b32 v255, s4, 28
	s_add_u32 s4, s6, 0x1d900000
	v_writelane_b32 v255, s4, 29
	s_addc_u32 s4, s7, 0
	v_writelane_b32 v255, s4, 30
	s_add_u32 s4, s6, 0x2d80100
	s_addc_u32 s5, s7, 0
	v_writelane_b32 v255, s4, 31
	s_nop 1
	v_writelane_b32 v255, s5, 32
	s_add_u32 s4, s6, 0x1c900100
	s_addc_u32 s5, s7, 0
	v_writelane_b32 v255, s4, 33
	s_nop 1
	v_writelane_b32 v255, s5, 34
	s_add_u32 s4, s6, 0x1d900100
	v_writelane_b32 v255, s4, 35
	s_addc_u32 s4, s7, 0
	v_writelane_b32 v255, s4, 36
	v_writelane_b32 v255, s24, 37
	v_writelane_b32 v255, s25, 38
	v_writelane_b32 v255, s26, 39
	s_branch .LBB0_809

; __global__ void __launch_bounds__(512, 2) hybrid_fwd(Params P) {
;     ...
;             for (;;) {
;                 __syncthreads();
;                 if (tid == 0) misc[0] = atomicAdd(ctl, 1u);
;                 __syncthreads();
;                 const int u = (int)misc[0];
;                 if (u >= 2048) break;
.LBB0_809:
	s_barrier
	s_and_saveexec_b64 s[6:7], s[44:45]
	s_cbranch_execz .LBB0_813
	v_readlane_b32 s4, v255, 63
	s_cmp_eq_u32 s4, 0
	s_cbranch_scc1 .Lq_fresh
	s_waitcnt vmcnt(0)
	v_mov_b32_e32 v0, v252
	s_branch .Lq_have
.Lq_fresh:
	v_mov_b32_e32 v1, 1
	global_atomic_add v0, v81, v1, s[38:39] sc0
	s_waitcnt vmcnt(0)
.Lq_have:
	ds_write_b32 v165, v0 offset:50688
	s_nop 1
	v_readfirstlane_b32 s4, v0
	s_mov_b32 s8, 0
	s_cmpk_ge_u32 s4, 0x500
	s_cbranch_scc1 .Lq_nopf
	v_mov_b32_e32 v1, 1
	global_atomic_add v252, v81, v1, s[38:39] sc0
	s_mov_b32 s8, 1
.Lq_nopf:
	v_writelane_b32 v255, s8, 63

; __global__ void __launch_bounds__(512, 2) hybrid_fwd(Params P) {
;     ...
;         { PHASE_BEGIN
;             for (int it = bx; it < 256; it += G)
;                 for (int i = 0; i < 4; ++i) { int tidu = tid; asm volatile("" : "+v"(tidu));
;                     branch_tile(lds, (const bf16_t*)(ws + WS_H), (const bf16_t*)(ws + WS_WBR), (const bf16_t*)(ws + WS_A), (bf16_t*)(ws + WS_B), it >> 1, 4 * (it & 1) + i, tidu); }
.LBB0_1085:
	s_nop 0
	s_nop 0
	s_nop 0
	s_nop 0
	s_nop 0
	s_nop 0
	s_or_b64 exec, exec, s[4:5]
	s_mov_b32 s4, s34
	s_barrier
	s_mov_b64 s[4:5], s[58:59]
	s_mov_b32 s16, s69
	s_mov_b32 s17, s2
	v_mov_b32_e32 v138, v146
	s_cmpk_gt_i32 s17, 0xff
	s_cbranch_scc1 .LBB0_1096
	s_add_u32 s18, s4, 0x3100000
	s_addc_u32 s19, s5, 0
	s_add_u32 s20, s4, 0xd00000
	s_addc_u32 s21, s5, 0
	s_add_u32 s6, s4, 0x7100000
	s_addc_u32 s7, s5, 0
	s_add_u32 s8, s4, 0x13100000
	s_addc_u32 s9, s5, 0
	s_branch .LBB0_1088
